# lora w/a tile loaders: all cur/prv/mu loads of the four chunks issued before the first wait (one memory round trip per tile load phase instead of four)
# baseline (speedup 1.0000x reference)
.LBB0_277:
	s_lshl_b32 s4, s0, 5
	s_and_b32 s4, s4, 0xffffff80
	v_add_u32_e32 v72, s4, v105
	s_movk_i32 s4, 0x1200
	v_mad_i64_i32 v[0:1], s[4:5], v72, s4, v[86:87]
	v_lshl_add_u64 v[0:1], v[0:1], 0, v[88:89]
	v_add_co_u32_e32 v2, vcc, 0x1000, v0
	s_movk_i32 s6, 0x4000
	s_nop 0
	v_addc_co_u32_e32 v3, vcc, 0, v1, vcc
	global_load_dwordx4 v[12:15], v[2:3], off
	v_cmp_gt_i32_e32 vcc, s6, v72
	s_mov_b64 s[4:5], 0x1000
	v_lshl_add_u64 v[0:1], v[0:1], 0, s[4:5]
	global_load_dwordx4 v[166:169], v[74:75], off offset:16
	global_load_dwordx4 v[170:173], v[74:75], off
	global_load_dwordx4 v[174:177], v[78:79], off offset:16
	global_load_dwordx4 v[178:181], v[78:79], off
	global_load_dwordx4 v[182:185], v[80:81], off offset:16
	global_load_dwordx4 v[186:189], v[80:81], off
	global_load_dwordx4 v[154:157], v[0:1], off offset:16
	global_load_dwordx4 v[158:161], v[0:1], off offset:32
	global_load_dwordx4 v[162:165], v[0:1], off offset:48
	v_cndmask_b32_e32 v2, 7, v110, vcc
	s_movk_i32 s4, 0x3fff
	v_and_b32_e32 v2, v2, v72
	v_cmp_lt_i32_e64 s[4:5], s4, v72
	v_cmp_ne_u32_e64 s[6:7], 0, v2
	s_and_saveexec_b64 s[14:15], s[6:7]
	s_xor_b64 s[60:61], exec, s[14:15]
	s_cbranch_execz .LBB0_279
	v_add_co_u32_e32 v2, vcc, 0xfffff000, v0
	s_nop 1
	v_addc_co_u32_e32 v3, vcc, -1, v1, vcc
	global_load_dwordx4 v[244:247], v[2:3], off offset:-496
	global_load_dwordx4 v[248:251], v[2:3], off offset:-480
	global_load_dwordx4 v[252:255], v[2:3], off offset:-464
	global_load_dwordx4 v[2:5], v[2:3], off offset:-512
	s_waitcnt vmcnt(0)
	v_lshlrev_b32_e32 v20, 16, v2
	v_and_b32_e32 v21, 0xffff0000, v2
	v_lshlrev_b32_e32 v22, 16, v3
	v_and_b32_e32 v23, 0xffff0000, v3
	v_lshlrev_b32_e32 v8, 16, v4
	v_and_b32_e32 v9, 0xffff0000, v4
	v_lshlrev_b32_e32 v10, 16, v5
	v_and_b32_e32 v11, 0xffff0000, v5

.LBB0_283:
	s_or_b64 exec, exec, s[60:61]
	v_mov_b32_e32 v24, v166
	v_mov_b32_e32 v25, v167
	v_mov_b32_e32 v26, v168
	v_mov_b32_e32 v27, v169
	v_mov_b32_e32 v28, v170
	v_mov_b32_e32 v29, v171
	v_mov_b32_e32 v30, v172
	v_mov_b32_e32 v31, v173
	v_mov_b32_e32 v40, v154
	v_mov_b32_e32 v41, v155
	v_mov_b32_e32 v42, v156
	v_mov_b32_e32 v43, v157
	s_and_saveexec_b64 s[14:15], s[6:7]
	s_xor_b64 s[60:61], exec, s[14:15]
	s_cbranch_execz .LBB0_285
	v_add_co_u32_e32 v2, vcc, 0xfffff000, v0
	s_nop 1
	v_addc_co_u32_e32 v3, vcc, -1, v1, vcc
	v_mov_b32_e32 v2, v244
	v_mov_b32_e32 v3, v245
	v_mov_b32_e32 v4, v246
	v_mov_b32_e32 v5, v247
	s_waitcnt vmcnt(0)
	v_lshlrev_b32_e32 v44, 16, v2
	v_and_b32_e32 v45, 0xffff0000, v2
	v_lshlrev_b32_e32 v46, 16, v3
	v_and_b32_e32 v47, 0xffff0000, v3
	v_lshlrev_b32_e32 v36, 16, v4
	v_and_b32_e32 v37, 0xffff0000, v4
	v_lshlrev_b32_e32 v38, 16, v5
	v_and_b32_e32 v39, 0xffff0000, v5

.LBB0_289:
	s_or_b64 exec, exec, s[60:61]
	v_mov_b32_e32 v48, v174
	v_mov_b32_e32 v49, v175
	v_mov_b32_e32 v50, v176
	v_mov_b32_e32 v51, v177
	v_mov_b32_e32 v52, v178
	v_mov_b32_e32 v53, v179
	v_mov_b32_e32 v54, v180
	v_mov_b32_e32 v55, v181
	v_mov_b32_e32 v56, v158
	v_mov_b32_e32 v57, v159
	v_mov_b32_e32 v58, v160
	v_mov_b32_e32 v59, v161
	s_and_saveexec_b64 s[14:15], s[6:7]
	s_xor_b64 s[60:61], exec, s[14:15]
	s_cbranch_execz .LBB0_291
	v_add_co_u32_e32 v2, vcc, 0xfffff000, v0
	s_nop 1
	v_addc_co_u32_e32 v3, vcc, -1, v1, vcc
	v_mov_b32_e32 v2, v248
	v_mov_b32_e32 v3, v249
	v_mov_b32_e32 v4, v250
	v_mov_b32_e32 v5, v251
	s_waitcnt vmcnt(0)
	v_lshlrev_b32_e32 v60, 16, v2
	v_and_b32_e32 v61, 0xffff0000, v2
	v_lshlrev_b32_e32 v62, 16, v3
	v_and_b32_e32 v63, 0xffff0000, v3
	v_lshlrev_b32_e32 v32, 16, v4
	v_and_b32_e32 v33, 0xffff0000, v4
	v_lshlrev_b32_e32 v34, 16, v5
	v_and_b32_e32 v35, 0xffff0000, v5

.LBB0_295:
	s_or_b64 exec, exec, s[60:61]
	v_mov_b32_e32 v64, v182
	v_mov_b32_e32 v65, v183
	v_mov_b32_e32 v66, v184
	v_mov_b32_e32 v67, v185
	v_mov_b32_e32 v68, v186
	v_mov_b32_e32 v69, v187
	v_mov_b32_e32 v70, v188
	v_mov_b32_e32 v71, v189
	v_mov_b32_e32 v16, v162
	v_mov_b32_e32 v17, v163
	v_mov_b32_e32 v18, v164
	v_mov_b32_e32 v19, v165
	s_and_saveexec_b64 s[14:15], s[6:7]
	s_xor_b64 s[6:7], exec, s[14:15]
	s_cbranch_execz .LBB0_297
	v_add_co_u32_e32 v0, vcc, 0xfffff000, v0
	s_nop 1
	v_addc_co_u32_e32 v1, vcc, -1, v1, vcc
	v_mov_b32_e32 v0, v252
	v_mov_b32_e32 v1, v253
	v_mov_b32_e32 v2, v254
	v_mov_b32_e32 v3, v255
	s_waitcnt vmcnt(0)
	v_lshlrev_b32_e32 v4, 16, v0
	v_and_b32_e32 v5, 0xffff0000, v0
	v_lshlrev_b32_e32 v6, 16, v1
	v_and_b32_e32 v7, 0xffff0000, v1
	v_lshlrev_b32_e32 v0, 16, v2
	v_and_b32_e32 v1, 0xffff0000, v2
	v_lshlrev_b32_e32 v2, 16, v3
	v_and_b32_e32 v3, 0xffff0000, v3

.LBB0_306:
	s_lshl_b32 s4, s0, 5
	s_and_b32 s4, s4, 0xffffff80
	v_add_u32_e32 v72, s4, v105
	s_movk_i32 s4, 0x1200
	v_mad_i64_i32 v[0:1], s[4:5], v72, s4, v[86:87]
	v_lshl_add_u64 v[4:5], v[0:1], 0, v[88:89]
	v_add_co_u32_e32 v0, vcc, 0x1000, v4
	s_movk_i32 s6, 0x4000
	s_nop 0
	v_addc_co_u32_e32 v1, vcc, 0, v5, vcc
	global_load_dwordx4 v[0:3], v[0:1], off offset:128
	s_mov_b64 s[4:5], 0x1080
	v_cmp_gt_i32_e32 vcc, s6, v72
	v_lshl_add_u64 v[32:33], v[4:5], 0, s[4:5]
	global_load_dwordx4 v[166:169], v[74:75], off offset:16
	global_load_dwordx4 v[170:173], v[74:75], off
	global_load_dwordx4 v[174:177], v[78:79], off offset:16
	global_load_dwordx4 v[178:181], v[78:79], off
	global_load_dwordx4 v[182:185], v[80:81], off offset:16
	global_load_dwordx4 v[186:189], v[80:81], off
	global_load_dwordx4 v[154:157], v[32:33], off offset:16
	global_load_dwordx4 v[158:161], v[32:33], off offset:32
	global_load_dwordx4 v[162:165], v[32:33], off offset:48
	s_movk_i32 s4, 0x3fff
	v_cndmask_b32_e32 v4, 7, v115, vcc
	v_and_b32_e32 v4, v4, v72
	v_cmp_lt_i32_e64 s[4:5], s4, v72
	v_cmp_ne_u32_e64 s[6:7], 0, v4
	s_and_saveexec_b64 s[14:15], s[6:7]
	s_xor_b64 s[56:57], exec, s[14:15]
	s_cbranch_execz .LBB0_308
	v_add_co_u32_e32 v4, vcc, 0xfffff000, v32
	s_nop 1
	v_addc_co_u32_e32 v5, vcc, -1, v33, vcc
	global_load_dwordx4 v[244:247], v[4:5], off offset:-496
	global_load_dwordx4 v[248:251], v[4:5], off offset:-480
	global_load_dwordx4 v[252:255], v[4:5], off offset:-464
	global_load_dwordx4 v[6:9], v[4:5], off offset:-512
	s_waitcnt vmcnt(0)
	v_lshlrev_b32_e32 v4, 16, v6
	v_and_b32_e32 v10, 0xffff0000, v6
	v_lshlrev_b32_e32 v5, 16, v7
	v_and_b32_e32 v11, 0xffff0000, v7
	v_lshlrev_b32_e32 v92, 16, v8
	v_and_b32_e32 v6, 0xffff0000, v8
	v_lshlrev_b32_e32 v93, 16, v9
	v_and_b32_e32 v7, 0xffff0000, v9

.LBB0_312:
	s_or_b64 exec, exec, s[56:57]
	v_mov_b32_e32 v12, v166
	v_mov_b32_e32 v13, v167
	v_mov_b32_e32 v14, v168
	v_mov_b32_e32 v15, v169
	v_mov_b32_e32 v16, v170
	v_mov_b32_e32 v17, v171
	v_mov_b32_e32 v18, v172
	v_mov_b32_e32 v19, v173
	v_mov_b32_e32 v44, v154
	v_mov_b32_e32 v45, v155
	v_mov_b32_e32 v46, v156
	v_mov_b32_e32 v47, v157
	s_and_saveexec_b64 s[14:15], s[6:7]
	s_xor_b64 s[56:57], exec, s[14:15]
	s_cbranch_execz .LBB0_314
	v_add_co_u32_e32 v8, vcc, 0xfffff000, v32
	s_nop 1
	v_addc_co_u32_e32 v9, vcc, -1, v33, vcc
	v_mov_b32_e32 v22, v244
	v_mov_b32_e32 v23, v245
	v_mov_b32_e32 v24, v246
	v_mov_b32_e32 v25, v247
	s_waitcnt vmcnt(0)
	v_lshlrev_b32_e32 v20, 16, v22
	v_and_b32_e32 v50, 0xffff0000, v22
	v_lshlrev_b32_e32 v21, 16, v23
	v_and_b32_e32 v51, 0xffff0000, v23
	v_lshlrev_b32_e32 v94, 16, v24
	v_and_b32_e32 v22, 0xffff0000, v24
	v_lshlrev_b32_e32 v95, 16, v25
	v_and_b32_e32 v23, 0xffff0000, v25

.LBB0_318:
	s_or_b64 exec, exec, s[56:57]
	v_mov_b32_e32 v28, v174
	v_mov_b32_e32 v29, v175
	v_mov_b32_e32 v30, v176
	v_mov_b32_e32 v31, v177
	v_mov_b32_e32 v52, v178
	v_mov_b32_e32 v53, v179
	v_mov_b32_e32 v54, v180
	v_mov_b32_e32 v55, v181
	v_mov_b32_e32 v56, v158
	v_mov_b32_e32 v57, v159
	v_mov_b32_e32 v58, v160
	v_mov_b32_e32 v59, v161
	s_and_saveexec_b64 s[14:15], s[6:7]
	s_xor_b64 s[56:57], exec, s[14:15]
	s_cbranch_execz .LBB0_320
	v_add_co_u32_e32 v8, vcc, 0xfffff000, v32
	s_nop 1
	v_addc_co_u32_e32 v9, vcc, -1, v33, vcc
	v_mov_b32_e32 v24, v248
	v_mov_b32_e32 v25, v249
	v_mov_b32_e32 v26, v250
	v_mov_b32_e32 v27, v251
	s_waitcnt vmcnt(0)
	v_lshlrev_b32_e32 v40, 16, v24
	v_and_b32_e32 v62, 0xffff0000, v24
	v_lshlrev_b32_e32 v41, 16, v25
	v_and_b32_e32 v63, 0xffff0000, v25
	v_lshlrev_b32_e32 v48, 16, v26
	v_and_b32_e32 v42, 0xffff0000, v26
	v_lshlrev_b32_e32 v49, 16, v27
	v_and_b32_e32 v43, 0xffff0000, v27

.LBB0_324:
	s_or_b64 exec, exec, s[56:57]
	v_mov_b32_e32 v64, v182
	v_mov_b32_e32 v65, v183
	v_mov_b32_e32 v66, v184
	v_mov_b32_e32 v67, v185
	v_mov_b32_e32 v68, v186
	v_mov_b32_e32 v69, v187
	v_mov_b32_e32 v70, v188
	v_mov_b32_e32 v71, v189
	v_mov_b32_e32 v36, v162
	v_mov_b32_e32 v37, v163
	v_mov_b32_e32 v38, v164
	v_mov_b32_e32 v39, v165
	s_and_saveexec_b64 s[14:15], s[6:7]
	s_xor_b64 s[6:7], exec, s[14:15]
	s_cbranch_execz .LBB0_326
	v_add_co_u32_e32 v8, vcc, 0xfffff000, v32
	s_nop 1
	v_addc_co_u32_e32 v9, vcc, -1, v33, vcc
	v_mov_b32_e32 v120, v252
	v_mov_b32_e32 v121, v253
	v_mov_b32_e32 v122, v254
	v_mov_b32_e32 v123, v255
	s_waitcnt vmcnt(0)
	v_lshlrev_b32_e32 v24, 16, v120
	v_and_b32_e32 v34, 0xffff0000, v120
	v_lshlrev_b32_e32 v25, 16, v121
	v_and_b32_e32 v35, 0xffff0000, v121
	v_lshlrev_b32_e32 v8, 16, v122
	v_and_b32_e32 v26, 0xffff0000, v122
	v_lshlrev_b32_e32 v9, 16, v123
	v_and_b32_e32 v27, 0xffff0000, v123
